# dead K/V address arithmetic removed from prompt attention; sample-attention sink load requested with the cache rows; LRU deferred scan reads all 32 a/b values from LDS up front
# baseline (speedup 1.0000x reference)
; __device__ __forceinline__ void attn_sample_item(const Params& P, LAS unsigned char* lds, int l, int db, int kvh, int tid_in) {
;     ...
;     const size_t cbase = (size_t)(l * 128 + db) * 128;
; #pragma unroll
;     for (int k = 0; k < 5; ++k) {
;         const int e = tid + 512 * k;
;         if (e < 132 * 16) {
;             const int key = e >> 4, d4 = (e & 15) * 4;
;             f32x4 kv, vv;
;             if (key < 128) { kv = *(const f32x4*)(P.in[I_CK] + ((cbase + key) * 2 + kvh) * 64 + d4); vv = *(const f32x4*)(P.in[I_CV] + ((cbase + key) * 2 + kvh) * 64 + d4); }
;             else { kv = *(const f32x4*)(P.out + O_WKS + ((cbase + key - 4) * 2 + kvh) * 64 + d4); vv = *(const f32x4*)(P.out + O_WVS + ((cbase + key - 4) * 2 + kvh) * 64 + d4); }
;     ...
;         const int row = wid * 2 + rr, g = row >> 2; const float sink = P.in[I_SINK][l * 8 + kvh * 4 + g];
.LBB0_954:
	s_cmpk_gt_i32 s14, 0x203
	s_mov_b64 s[0:1], -1
	s_cbranch_scc0 .LBB0_1019
	s_add_i32 s0, s14, 0xfffffdfc
	v_mov_b32_e32 v8, v216
	s_lshr_b32 s16, s0, 1
	s_and_b32 s15, s14, 1
	s_add_i32 s68, s16, s12
	s_lshl_b32 s0, s15, 2
	v_ashrrev_i32_e32 v202, 7, v8
	s_or_b32 s0, s0, s13
	v_add_u32_e32 v202, s0, v202
	v_ashrrev_i32_e32 v203, 31, v202
	v_lshl_add_u64 v[202:203], v[202:203], 2, s[54:55]
	global_load_dword v200, v[202:203], off
	s_movk_i32 s0, 0x840
	v_cmp_gt_i32_e32 vcc, s0, v8
	s_lshl_b32 s4, s68, 7
	v_lshlrev_b32_e32 v11, 2, v8
	v_and_b32_e32 v9, 60, v11
	v_lshlrev_b32_e32 v10, 2, v9
	v_lshrrev_b32_e32 v12, 4, v8
	v_add_u32_e32 v14, s4, v12
	v_lshlrev_b32_e32 v14, 9, v14
	s_lshl_b32 s5, s15, 8
	v_add3_u32 v14, v14, s5, v10
	v_mov_b32_e32 v15, 0
	v_readlane_b32 s40, v252, 29
	v_readlane_b32 s41, v252, 30
	v_readlane_b32 s42, v252, 31
	v_readlane_b32 s43, v252, 32
	v_readlane_b32 s44, v254, 10
	v_readlane_b32 s45, v254, 11
	v_readlane_b32 s46, v254, 14
	v_readlane_b32 s47, v254, 15
	s_mov_b64 s[2:3], 0x4000
	v_readfirstlane_b32 s17, v8
	s_nop 1
	v_lshl_add_u64 v[16:17], s[40:41], 0, v[14:15]
	v_lshl_add_u64 v[26:27], s[42:43], 0, v[14:15]
	global_load_dwordx4 v[48:51], v[16:17], off
	global_load_dwordx4 v[68:71], v[26:27], off
	v_lshl_add_u64 v[18:19], v[16:17], 0, s[2:3]
	v_lshl_add_u64 v[28:29], v[26:27], 0, s[2:3]
	global_load_dwordx4 v[52:55], v[18:19], off
	global_load_dwordx4 v[72:75], v[28:29], off
	v_lshl_add_u64 v[20:21], v[18:19], 0, s[2:3]
	v_lshl_add_u64 v[30:31], v[28:29], 0, s[2:3]
	global_load_dwordx4 v[56:59], v[20:21], off
	global_load_dwordx4 v[76:79], v[30:31], off
	v_lshl_add_u64 v[22:23], v[20:21], 0, s[2:3]
	v_lshl_add_u64 v[32:33], v[30:31], 0, s[2:3]
	global_load_dwordx4 v[60:63], v[22:23], off
	global_load_dwordx4 v[84:87], v[32:33], off
	v_lshl_add_u64 v[16:17], s[44:45], 0, v[14:15]
	v_lshl_add_u64 v[26:27], s[46:47], 0, v[14:15]
	s_cmp_lt_u32 s17, 64
	s_cbranch_scc0 .Lsa_no_k4
	s_mov_b64 s[8:9], 0x10000
	v_lshl_add_u64 v[24:25], v[16:17], 0, s[8:9]
	v_lshl_add_u64 v[34:35], v[26:27], 0, s[8:9]
	global_load_dwordx4 v[64:67], v[24:25], off offset:-2048
	global_load_dwordx4 v[88:91], v[34:35], off offset:-2048

; __device__ __forceinline__ void attn_sample_item(const Params& P, LAS unsigned char* lds, int l, int db, int kvh, int tid_in) {
;     ...
;     for (int rr = 0; rr < 2; ++rr) {
;         const int row = wid * 2 + rr, g = row >> 2; const float sink = P.in[I_SINK][l * 8 + kvh * 4 + g];
;         float v0 = S[row * 132 + lane], v1 = S[row * 132 + 64 + lane], v2 = lane < 4 ? S[row * 132 + 128 + lane] : -1e30f;
;         float mx = fmaxf(fmaxf(v0, v1), fmaxf(v2, sink));
; #pragma unroll
;         for (int o = 1; o < 64; o <<= 1) mx = fmaxf(mx, __shfl_xor(mx, o));
;         const float p0 = v0 > -1e29f ? __expf(v0 - mx) : 0.f, p1 = v1 > -1e29f ? __expf(v1 - mx) : 0.f, p2 = v2 > -1e29f ? __expf(v2 - mx) : 0.f;
;         float sum = p0 + p1 + p2;
; #pragma unroll
;         for (int o = 1; o < 64; o <<= 1) sum += __shfl_xor(sum, o);
;         const float inv = 1.f / (sum + __expf(sink - mx));
;         S[row * 132 + lane] = p0 * inv; S[row * 132 + 64 + lane] = p1 * inv; if (lane < 4) S[row * 132 + 128 + lane] = p2 * inv;
;     }
.LBB0_1005:
	s_or_b64 exec, exec, s[2:3]
	s_lshl_b32 s0, s15, 2
	v_ashrrev_i32_e32 v1, 7, v8
	s_or_b32 s0, s0, s13
	v_add_u32_e32 v2, s0, v1
	v_ashrrev_i32_e32 v3, 31, v2
	v_lshl_add_u64 v[2:3], v[2:3], 2, s[54:55]
	s_waitcnt lgkmcnt(0)
	s_barrier
	v_ashrrev_i32_e32 v4, 5, v8
	v_and_b32_e32 v2, 0xffffffe, v4
	v_mul_lo_u32 v2, v2, s57
	s_add_i32 s2, 0, 0x11a10
	v_lshlrev_b32_e32 v5, 2, v0
	v_add3_u32 v7, s2, v2, v5
	ds_read2st64_b32 v[2:3], v7 offset1:1
	v_cmp_gt_u32_e64 s[38:39], 4, v0
	v_mov_b32_e32 v9, 0xf149f2ca
	s_and_saveexec_b64 s[0:1], s[38:39]
	ds_read_b32 v9, v7 offset:512
	s_or_b64 exec, exec, s[0:1]
	s_waitcnt vmcnt(0)
	v_max_f32_e32 v6, v200, v200
	s_waitcnt lgkmcnt(0)
	v_max_f32_e32 v10, v9, v9
	v_max_f32_e32 v10, v10, v6
	v_max3_f32 v10, v2, v3, v10
	ds_bpermute_b32 v11, v217, v10
	v_cmp_lt_f32_e32 vcc, s35, v2
	s_waitcnt lgkmcnt(0)
	v_max_f32_e32 v11, v11, v11
	v_max_f32_e32 v10, v10, v11
	ds_bpermute_b32 v11, v218, v10
	s_waitcnt lgkmcnt(0)
	v_max_f32_e32 v11, v11, v11
	v_max_f32_e32 v10, v10, v11
	ds_bpermute_b32 v11, v219, v10
	s_waitcnt lgkmcnt(0)
	v_max_f32_e32 v11, v11, v11
	v_max_f32_e32 v10, v10, v11
	ds_bpermute_b32 v11, v220, v10
	s_waitcnt lgkmcnt(0)
	v_max_f32_e32 v11, v11, v11
	v_max_f32_e32 v10, v10, v11
	ds_bpermute_b32 v11, v221, v10
	s_waitcnt lgkmcnt(0)
	v_max_f32_e32 v11, v11, v11
	v_max_f32_e32 v10, v10, v11
	ds_bpermute_b32 v11, v222, v10
	s_waitcnt lgkmcnt(0)
	v_max_f32_e32 v11, v11, v11
	v_max_f32_e32 v10, v10, v11
	v_sub_f32_e32 v11, v2, v10
	v_sub_f32_e32 v12, v3, v10
	v_mul_f32_e32 v11, 0x3fb8aa3b, v11
	v_sub_f32_e32 v13, v9, v10
	v_mul_f32_e32 v12, 0x3fb8aa3b, v12
	v_exp_f32_e32 v11, v11
	v_mul_f32_e32 v13, 0x3fb8aa3b, v13
	v_exp_f32_e32 v12, v12
	v_exp_f32_e32 v13, v13
	v_cndmask_b32_e32 v11, 0, v11, vcc
	v_cmp_lt_f32_e32 vcc, s35, v3
	v_sub_f32_e32 v10, v1, v10
	v_mul_f32_e32 v10, 0x3fb8aa3b, v10
	v_cndmask_b32_e32 v12, 0, v12, vcc
	v_cmp_lt_f32_e32 vcc, s35, v9
	v_add_f32_e32 v3, v11, v12
	v_exp_f32_e32 v10, v10
	v_cndmask_b32_e32 v2, 0, v13, vcc
	v_add_f32_e32 v3, v2, v3
	ds_bpermute_b32 v9, v217, v3
	s_waitcnt lgkmcnt(0)
	v_add_f32_e32 v3, v3, v9
	ds_bpermute_b32 v9, v218, v3
	s_waitcnt lgkmcnt(0)
	v_add_f32_e32 v3, v3, v9
	ds_bpermute_b32 v9, v219, v3
	s_waitcnt lgkmcnt(0)
	v_add_f32_e32 v3, v3, v9
	ds_bpermute_b32 v9, v220, v3
	s_waitcnt lgkmcnt(0)
	v_add_f32_e32 v3, v3, v9
	ds_bpermute_b32 v9, v221, v3
	s_waitcnt lgkmcnt(0)
	v_add_f32_e32 v3, v3, v9
	ds_bpermute_b32 v9, v222, v3
	s_waitcnt lgkmcnt(0)
	v_add_f32_e32 v3, v3, v9
	v_add_f32_e32 v3, v10, v3
	v_div_scale_f32 v9, s[0:1], v3, v3, 1.0
	v_rcp_f32_e32 v10, v9
	v_div_scale_f32 v13, vcc, 1.0, v3, 1.0
	v_fma_f32 v14, -v9, v10, 1.0
	v_fmac_f32_e32 v10, v14, v10
	v_mul_f32_e32 v14, v13, v10
	v_fma_f32 v15, -v9, v14, v13
	v_fmac_f32_e32 v14, v15, v10
	v_fma_f32 v9, -v9, v14, v13
	v_div_fmas_f32 v9, v9, v10, v14
	v_div_fixup_f32 v3, v9, v3, 1.0
	v_mul_f32_e32 v9, v11, v3
	v_mul_f32_e32 v10, v12, v3
	ds_write2st64_b32 v7, v9, v10 offset1:1
	s_and_saveexec_b64 s[0:1], s[38:39]
	v_mul_f32_e32 v2, v2, v3
	ds_write_b32 v7, v2 offset:512
	s_or_b64 exec, exec, s[0:1]
	v_or_b32_e32 v2, 1, v4
	v_mul_lo_u32 v2, v2, s57
	v_add3_u32 v4, s2, v2, v5
	ds_read2st64_b32 v[2:3], v4 offset1:1
	v_mov_b32_e32 v5, 0xf149f2ca
	s_and_saveexec_b64 s[0:1], s[38:39]
	ds_read_b32 v5, v4 offset:512
	s_or_b64 exec, exec, s[0:1]
	s_waitcnt lgkmcnt(0)
	v_max_f32_e32 v7, v5, v5
	v_max_f32_e32 v6, v7, v6
	v_max3_f32 v6, v2, v3, v6
	ds_bpermute_b32 v7, v217, v6
	v_cmp_lt_f32_e32 vcc, s35, v2
	s_waitcnt lgkmcnt(0)
	v_max_f32_e32 v7, v7, v7
	v_max_f32_e32 v6, v6, v7
	ds_bpermute_b32 v7, v218, v6
	s_waitcnt lgkmcnt(0)
	v_max_f32_e32 v7, v7, v7
	v_max_f32_e32 v6, v6, v7
	ds_bpermute_b32 v7, v219, v6
	s_waitcnt lgkmcnt(0)
	v_max_f32_e32 v7, v7, v7
	v_max_f32_e32 v6, v6, v7
	ds_bpermute_b32 v7, v220, v6
	s_waitcnt lgkmcnt(0)
	v_max_f32_e32 v7, v7, v7
	v_max_f32_e32 v6, v6, v7
	ds_bpermute_b32 v7, v221, v6
	s_waitcnt lgkmcnt(0)
	v_max_f32_e32 v7, v7, v7
	v_max_f32_e32 v6, v6, v7
	ds_bpermute_b32 v7, v222, v6
	s_waitcnt lgkmcnt(0)
	v_max_f32_e32 v7, v7, v7
	v_max_f32_e32 v6, v6, v7
	v_sub_f32_e32 v7, v2, v6
	v_sub_f32_e32 v9, v3, v6
	v_mul_f32_e32 v7, 0x3fb8aa3b, v7
	v_sub_f32_e32 v10, v5, v6
	v_mul_f32_e32 v9, 0x3fb8aa3b, v9
	v_exp_f32_e32 v7, v7
	v_mul_f32_e32 v10, 0x3fb8aa3b, v10
	v_exp_f32_e32 v9, v9
	v_exp_f32_e32 v10, v10
	v_cndmask_b32_e32 v7, 0, v7, vcc
	v_cmp_lt_f32_e32 vcc, s35, v3
	v_sub_f32_e32 v1, v1, v6
	v_mul_f32_e32 v1, 0x3fb8aa3b, v1
	v_cndmask_b32_e32 v3, 0, v9, vcc
	v_cmp_lt_f32_e32 vcc, s35, v5
	v_add_f32_e32 v5, v7, v3
	v_exp_f32_e32 v1, v1
	v_cndmask_b32_e32 v2, 0, v10, vcc
	v_add_f32_e32 v5, v2, v5
	ds_bpermute_b32 v9, v217, v5
	s_waitcnt lgkmcnt(0)
	v_add_f32_e32 v5, v5, v9
	ds_bpermute_b32 v9, v218, v5
	s_waitcnt lgkmcnt(0)
	v_add_f32_e32 v5, v5, v9
	ds_bpermute_b32 v9, v219, v5
	s_waitcnt lgkmcnt(0)
	v_add_f32_e32 v5, v5, v9
	ds_bpermute_b32 v9, v220, v5
	s_waitcnt lgkmcnt(0)
	v_add_f32_e32 v5, v5, v9
	ds_bpermute_b32 v9, v221, v5
	s_waitcnt lgkmcnt(0)
	v_add_f32_e32 v5, v5, v9
	ds_bpermute_b32 v6, v222, v5
	s_waitcnt lgkmcnt(0)
	v_add_f32_e32 v5, v5, v6
	v_add_f32_e32 v1, v1, v5
	v_div_scale_f32 v5, s[0:1], v1, v1, 1.0
	v_rcp_f32_e32 v6, v5
	v_div_scale_f32 v9, vcc, 1.0, v1, 1.0
	v_fma_f32 v10, -v5, v6, 1.0
	v_fmac_f32_e32 v6, v10, v6
	v_mul_f32_e32 v10, v9, v6
	v_fma_f32 v11, -v5, v10, v9
	v_fmac_f32_e32 v10, v11, v6
	v_fma_f32 v5, -v5, v10, v9
	v_div_fmas_f32 v5, v5, v6, v10
	v_div_fixup_f32 v1, v5, v1, 1.0
	v_mul_f32_e32 v5, v7, v1
	v_mul_f32_e32 v3, v3, v1
	ds_write2st64_b32 v4, v5, v3 offset1:1
	s_and_saveexec_b64 s[0:1], s[38:39]
	v_mul_f32_e32 v1, v2, v1
	ds_write_b32 v4, v1 offset:512
	s_or_b64 exec, exec, s[0:1]
	s_waitcnt lgkmcnt(0)
	s_barrier
	s_and_saveexec_b64 s[2:3], s[36:37]
	s_cbranch_execz .LBB0_1018
	s_lshl_b32 s0, s16, 2
	v_mov_b32_e32 v1, 0x8610
	s_addk_i32 s0, 0x4080
	s_lshl_b32 s1, s15, 8
	v_lshl_add_u32 v2, v0, 2, v1
	s_mov_b64 s[4:5], 0
	v_lshlrev_b32_e32 v0, 1, v0

; __device__ __forceinline__ void attn_prompt_wave(const Params& P, int l, int qt, int tid_in) {
;     const int tid = tid_in, lane = tid & 63, l32 = lane & 31, h = lane >> 5, head = tid >> 6, kvh = head >> 2;
;     const bf16* Q = (const bf16*)((const unsigned char*)P.out + OB_Q); bf16* ATT = (bf16*)((unsigned char*)P.out + OB_ATT);
;     const bf16* KB = (const bf16*)(P.ws + WS_KB); const bf16* VT = (const bf16*)(P.ws + WS_VT);
;     const int q0 = qt * 32, key0 = q0 - 128;
;     bf16x8 qf[4];
; #pragma unroll
;     for (int kk = 0; kk < 4; ++kk) qf[kk] = *(const bf16x8*)(Q + (size_t)(q0 + l32) * 512 + head * 64 + kk * 16 + h * 8);
;     bf16x8 kf[5][4];
; #pragma unroll
;     for (int kb = 0; kb < 5; ++kb) {
;         int krow_ = key0 + kb * 32 + l32; krow_ = krow_ < 0 ? 0 : krow_;
;         const bf16* kp = KB + (size_t)krow_ * 128 + kvh * 64 + h * 8;
; #pragma unroll
;         for (int kk = 0; kk < 4; ++kk) kf[kb][kk] = *(const bf16x8*)(kp + kk * 16);
;     }
;     u32x2 vfa[5][2][2], vfb[5][2][2];
; #pragma unroll
;     for (int kb = 0; kb < 5; ++kb)
; #pragma unroll
;         for (int s = 0; s < 2; ++s) {
;             int k0 = key0 + kb * 32 + 16 * s + 4 * h, k1 = k0 + 8; k0 = k0 < 0 ? 0 : k0; k1 = k1 < 0 ? 0 : k1;
; #pragma unroll
;             for (int db = 0; db < 2; ++db) {
;                 const bf16* vp = VT + ((size_t)kvh * (MP / 4) * 64 + db * 32 + l32) * 4;
;                 vfa[kb][s][db] = *(const u32x2*)(vp + (size_t)(k0 >> 2) * 256); vfb[kb][s][db] = *(const u32x2*)(vp + (size_t)(k1 >> 2) * 256);
;             }
;         }
.LBB0_1019:
	s_and_b64 vcc, exec, s[0:1]
	s_cbranch_vccz .LBB0_953
	s_lshl_b32 s0, s14, 5
	v_readlane_b32 s2, v254, 0
	v_readlane_b32 s3, v254, 1
	v_readlane_b32 s18, v254, 2
	v_readlane_b32 s19, v254, 3
	v_and_b32_e32 v72, 7, v216
	v_bfe_u32 v73, v216, 3, 5
	v_ashrrev_i32_e32 v74, 8, v216
	v_lshlrev_b32_e32 v75, 4, v72
	s_addk_i32 s0, 0xff80
	v_lshl_or_b32 v75, v74, 7, v75
	v_add_u32_e32 v64, s0, v73
	v_mul_u32_u24_e32 v68, 0x90, v73
	v_mul_u32_u24_e32 v73, 0x5a00, v74
	v_lshl_add_u32 v68, v72, 4, v68
	v_add_u32_e32 v68, v68, v73
	v_max_i32_e32 v65, 0, v64
	v_lshl_add_u32 v65, v65, 8, v75
	global_load_dwordx4 v[28:31], v65, s[2:3]
	v_add_u32_e32 v65, 32, v64
	v_max_i32_e32 v65, 0, v65
	v_lshl_add_u32 v65, v65, 8, v75
	global_load_dwordx4 v[24:27], v65, s[2:3]
	v_add_u32_e32 v65, 64, v64
	v_max_i32_e32 v65, 0, v65
	v_lshl_add_u32 v65, v65, 8, v75
	global_load_dwordx4 v[16:19], v65, s[2:3]
	v_add_u32_e32 v65, 96, v64
	v_max_i32_e32 v65, 0, v65
	v_lshl_add_u32 v65, v65, 8, v75
	global_load_dwordx4 v[20:23], v65, s[2:3]
	v_add_u32_e32 v65, 128, v64
	v_max_i32_e32 v65, 0, v65
	v_lshl_add_u32 v65, v65, 8, v75
	global_load_dwordx4 v[76:79], v65, s[2:3]
	s_lshl_b32 s1, s14, 3
	v_bfe_u32 v72, v216, 5, 3
	v_and_b32_e32 v73, 31, v216
	s_sub_i32 s1, s1, 32
	v_mul_u32_u24_e32 v75, 0x218000, v74
	v_lshlrev_b32_e32 v73, 4, v73
	v_add_u32_e32 v72, s1, v72
	v_add_u32_e32 v73, v73, v75
	v_and_b32_e32 v201, 0xff, v216
	v_mul_u32_u24_e32 v75, 0x5000, v74
	v_lshlrev_b32_e32 v201, 4, v201
	v_add_u32_e32 v75, 0xb400, v75
	v_add_u32_e32 v201, v201, v75
	v_bfe_u32 v200, v216, 5, 1
	v_and_b32_e32 v66, 31, v216
	v_lshlrev_b32_e32 v200, 9, v200
	v_lshl_add_u32 v200, v66, 3, v200
	v_add_u32_e32 v200, v200, v75
	v_max_i32_e32 v65, 0, v72
	v_lshl_add_u32 v65, v65, 9, v73
	global_load_dwordx4 v[204:207], v65, s[18:19]
	v_add_u32_e32 v65, 8, v72
	v_max_i32_e32 v65, 0, v65
	v_lshl_add_u32 v65, v65, 9, v73
	global_load_dwordx4 v[208:211], v65, s[18:19]
	v_add_u32_e32 v65, 16, v72
	v_max_i32_e32 v65, 0, v65
	v_lshl_add_u32 v65, v65, 9, v73
	global_load_dwordx4 v[212:215], v65, s[18:19]
	v_add_u32_e32 v65, 24, v72
	v_max_i32_e32 v65, 0, v65
	v_lshl_add_u32 v65, v65, 9, v73
	global_load_dwordx4 v[234:237], v65, s[18:19]
	v_add_u32_e32 v65, 32, v72
	v_max_i32_e32 v65, 0, v65
	v_lshl_add_u32 v65, v65, 9, v73
	global_load_dwordx4 v[238:241], v65, s[18:19]
	v_mov_b32_e32 v10, v216
	s_lshl_b32 s0, s14, 5
	v_and_b32_e32 v11, 31, v10
	v_or_b32_e32 v182, s0, v11
	v_readlane_b32 s2, v254, 0
	v_bfe_u32 v12, v10, 5, 1
	v_ashrrev_i32_e32 v183, 31, v182
	v_readlane_b32 s36, v252, 1
	s_add_i32 s1, s0, 0xffffff80
	v_readlane_b32 s3, v254, 1
	v_lshlrev_b64 v[178:179], 10, v[182:183]
	v_readlane_b32 s38, v252, 3
	v_readlane_b32 s39, v252, 4
	v_lshlrev_b32_e32 v80, 4, v12
	s_cmp_lt_i32 s14, 4
	v_lshl_add_u64 v[4:5], s[38:39], 0, v[178:179]
	s_cselect_b64 s[38:39], -1, 0
	v_and_b32_e32 v180, 0xffffffc0, v10
	v_ashrrev_i32_e32 v181, 31, v180
	v_lshl_add_u64 v[4:5], v[180:181], 1, v[4:5]
	v_lshl_add_u64 v[4:5], v[4:5], 0, v[80:81]
	global_load_dwordx4 v[32:35], v[4:5], off
	global_load_dwordx4 v[90:93], v[4:5], off offset:32
	global_load_dwordx4 v[166:169], v[4:5], off offset:64
	global_load_dwordx4 v[162:165], v[4:5], off offset:96
	s_add_i32 s17, s0, 0xffffffa0
	v_readlane_b32 s37, v252, 2
	s_cmp_lt_i32 s14, 3
	s_cselect_b64 s[36:37], -1, 0
	s_sub_i32 s16, s0, 64
	s_cmp_lt_i32 s14, 2
	s_cselect_b64 s[8:9], -1, 0
	s_sub_i32 s15, s0, 32
	s_cmp_lt_i32 s14, 1
	s_cselect_b64 s[4:5], -1, 0
	s_cmp_lt_i32 s14, 0
	s_cselect_b64 s[2:3], -1, 0
	v_lshlrev_b32_e32 v80, 2, v12
	v_readlane_b32 s18, v254, 2
	v_or_b32_e32 v183, s1, v80
	v_readlane_b32 s19, v254, 3
	v_ashrrev_i32_e32 v190, 6, v10
	s_waitcnt vmcnt(4)
	ds_write_b128 v68, v[28:31]
	ds_write_b128 v68, v[24:27] offset:4608
	ds_write_b128 v68, v[16:19] offset:9216
	ds_write_b128 v68, v[20:23] offset:13824
	ds_write_b128 v68, v[76:79] offset:18432
	ds_write_b128 v201, v[204:207]
	ds_write_b128 v201, v[208:211] offset:4096
	ds_write_b128 v201, v[212:215] offset:8192
	ds_write_b128 v201, v[234:237] offset:12288
	ds_write_b128 v201, v[238:241] offset:16384
	v_and_b32_e32 v170, 31, v216
	v_bfe_u32 v171, v216, 5, 1
	v_mul_u32_u24_e32 v170, 0x90, v170
	v_ashrrev_i32_e32 v172, 8, v216
	v_lshl_add_u32 v170, v171, 4, v170
	v_mul_u32_u24_e32 v172, 0x5a00, v172
	s_nop 0
	v_add_u32_e32 v170, v170, v172
	s_waitcnt lgkmcnt(0)
	s_barrier
; #define MFMA32(a, b, c) __builtin_amdgcn_mfma_f32_32x32x16_bf16((a), (b), (c), 0, 0, 0)
; __device__ __forceinline__ void attn_prompt_wave(const Params& P, int l, int qt, int tid_in) {
;     ...
;     f32x16 st[5];
; #pragma unroll
;     for (int kb = 0; kb < 5; ++kb) {
; #pragma unroll
;         for (int i = 0; i < 16; ++i) st[kb][i] = 0.f;
; #pragma unroll
;         for (int kk = 0; kk < 4; ++kk) st[kb] = MFMA32(kf[kb][kk], qf[kk], st[kb]);
;     }
;     const int qi = q0 + l32, bstart = (qi / LP) * LP;
;     const float sink = P.in[I_SINK][l * 8 + head];
;     float mx = sink;
;     const bool interior = key0 >= (q0 / LP) * LP && (q0 + 31) / LP == q0 / LP;
	ds_read_b128 v[0:3], v170
	ds_read_b128 v[28:31], v170 offset:32
	ds_read_b128 v[24:27], v170 offset:64
	ds_read_b128 v[16:19], v170 offset:96
	ds_read_b128 v[20:23], v170 offset:4608
	ds_read_b128 v[76:79], v170 offset:4640
	ds_read_b128 v[72:75], v170 offset:4672
	ds_read_b128 v[64:67], v170 offset:4704
	ds_read_b128 v[68:71], v170 offset:9216
	ds_read_b128 v[60:63], v170 offset:9248
	ds_read_b128 v[56:59], v170 offset:9280
	ds_read_b128 v[48:51], v170 offset:9312
	ds_read_b128 v[52:55], v170 offset:13824
	ds_read_b128 v[98:101], v170 offset:13856
	ds_read_b128 v[44:47], v170 offset:13888
	ds_read_b128 v[36:39], v170 offset:13920
	ds_read_b128 v[40:43], v170 offset:18432
	ds_read_b128 v[94:97], v170 offset:18464
	ds_read_b128 v[174:177], v170 offset:18496
	ds_read_b128 v[170:173], v170 offset:18528
	ds_read_b64 v[86:87], v200
	ds_read_b64 v[88:89], v200 offset:1024
	ds_read_b64 v[84:85], v200 offset:1280
	ds_read_b64 v[82:83], v200 offset:256
	s_waitcnt vmcnt(3)
	s_waitcnt lgkmcnt(4)
	v_mfma_f32_32x32x16_bf16 v[0:15], v[0:3], v[32:35], 0
	ds_read_b64 v[158:159], v200 offset:2048
	ds_read_b64 v[160:161], v200 offset:3072
	ds_read_b64 v[156:157], v200 offset:3328
	ds_read_b64 v[154:155], v200 offset:2304
	s_waitcnt vmcnt(2)
	v_mfma_f32_32x32x16_bf16 v[0:15], v[28:31], v[90:93], v[0:15]
	v_readlane_b32 s40, v252, 5
	v_readlane_b32 s41, v252, 6
	v_readlane_b32 s42, v252, 7
	s_waitcnt vmcnt(0)
	v_mfma_f32_32x32x16_bf16 v[0:15], v[24:27], v[166:169], v[0:15]
	s_waitcnt vmcnt(0)
	v_mfma_f32_32x32x16_bf16 v[0:15], v[16:19], v[162:165], v[0:15]
	ds_read_b64 v[150:151], v200 offset:4096
	ds_read_b64 v[152:153], v200 offset:5120
	ds_read_b64 v[148:149], v200 offset:5376
	ds_read_b64 v[146:147], v200 offset:4352
	s_waitcnt vmcnt(0)
	v_mfma_f32_32x32x16_bf16 v[16:31], v[20:23], v[32:35], 0
	ds_read_b64 v[142:143], v200 offset:6144
	ds_read_b64 v[144:145], v200 offset:7168
	ds_read_b64 v[140:141], v200 offset:7424
	ds_read_b64 v[138:139], v200 offset:6400
	v_readlane_b32 s43, v252, 8
	s_waitcnt vmcnt(0)
	v_mfma_f32_32x32x16_bf16 v[16:31], v[76:79], v[90:93], v[16:31]
	s_waitcnt vmcnt(0)
	v_mfma_f32_32x32x16_bf16 v[16:31], v[72:75], v[166:169], v[16:31]
	s_waitcnt vmcnt(0)
	v_mfma_f32_32x32x16_bf16 v[16:31], v[64:67], v[162:165], v[16:31]
	ds_read_b64 v[134:135], v200 offset:8192
	ds_read_b64 v[136:137], v200 offset:9216
	ds_read_b64 v[132:133], v200 offset:9472
	ds_read_b64 v[130:131], v200 offset:8448
	s_waitcnt vmcnt(0)
	v_mfma_f32_32x32x16_bf16 v[64:79], v[68:71], v[32:35], 0
	s_waitcnt vmcnt(0)
	v_mfma_f32_32x32x16_bf16 v[64:79], v[60:63], v[90:93], v[64:79]
	ds_read_b64 v[126:127], v200 offset:10240
	ds_read_b64 v[128:129], v200 offset:11264
	ds_read_b64 v[124:125], v200 offset:11520
	ds_read_b64 v[122:123], v200 offset:10496
	s_waitcnt vmcnt(0)
	v_mfma_f32_32x32x16_bf16 v[64:79], v[56:59], v[166:169], v[64:79]
	s_waitcnt vmcnt(0)
	v_mfma_f32_32x32x16_bf16 v[64:79], v[48:51], v[162:165], v[64:79]
	ds_read_b64 v[118:119], v200 offset:12288
	ds_read_b64 v[120:121], v200 offset:13312
	ds_read_b64 v[116:117], v200 offset:13568
	ds_read_b64 v[114:115], v200 offset:12544
	s_waitcnt vmcnt(0)
	v_mfma_f32_32x32x16_bf16 v[48:63], v[52:55], v[32:35], 0
	s_waitcnt vmcnt(0)
	v_mfma_f32_32x32x16_bf16 v[48:63], v[98:101], v[90:93], v[48:63]
	ds_read_b64 v[110:111], v200 offset:14336
	ds_read_b64 v[112:113], v200 offset:15360
	ds_read_b64 v[108:109], v200 offset:15616
	ds_read_b64 v[106:107], v200 offset:14592
	s_waitcnt vmcnt(0)
	v_mfma_f32_32x32x16_bf16 v[48:63], v[44:47], v[166:169], v[48:63]
	s_waitcnt vmcnt(0)
	v_mfma_f32_32x32x16_bf16 v[48:63], v[36:39], v[162:165], v[48:63]
	ds_read_b64 v[102:103], v200 offset:16384
	ds_read_b64 v[104:105], v200 offset:17408
	ds_read_b64 v[100:101], v200 offset:17664
	ds_read_b64 v[98:99], v200 offset:16640
	s_waitcnt vmcnt(0)
	v_mfma_f32_32x32x16_bf16 v[32:47], v[40:43], v[32:35], 0
	s_mul_hi_i32 s2, s0, 0xfe03f81
	s_lshr_b32 s3, s2, 31
	s_ashr_i32 s4, s2, 7
	s_add_i32 s4, s4, s3
	s_mul_i32 s2, s4, 0x810
	s_waitcnt vmcnt(0)
	v_mfma_f32_32x32x16_bf16 v[32:47], v[94:97], v[90:93], v[32:47]
	ds_read_b64 v[94:95], v200 offset:18432
	ds_read_b64 v[96:97], v200 offset:19456
	ds_read_b64 v[92:93], v200 offset:19712
	s_nop 0
	ds_read_b64 v[90:91], v200 offset:18688
	s_cmp_lt_i32 s1, s2
	s_mov_b64 s[2:3], 0
	s_waitcnt vmcnt(0)
	v_mfma_f32_32x32x16_bf16 v[32:47], v[174:177], v[166:169], v[32:47]
	v_add_u32_e32 v166, s13, v190
	v_ashrrev_i32_e32 v167, 31, v166
	v_lshl_add_u64 v[166:167], v[166:167], 2, s[54:55]
	global_load_dword v166, v[166:167], off
	s_waitcnt vmcnt(1)
	v_mfma_f32_32x32x16_bf16 v[32:47], v[170:173], v[162:165], v[32:47]
	s_cbranch_scc1 .LBB0_1022
	s_or_b32 s0, s0, 31
	s_mul_hi_i32 s0, s0, 0xfe03f81
	s_lshr_b32 s1, s0, 31
	s_ashr_i32 s0, s0, 7
	s_add_i32 s0, s0, s1
	s_cmp_eq_u32 s0, s4
	s_cselect_b64 s[2:3], -1, 0

; template <int MODE> __device__ __forceinline__ void lru_phase(const Params& P, LAS unsigned char* lds, int l, int tid_in) {
;     ...
;         if (prev >= 0) {
;             const int pos0 = psamp ? 0 : ((pt0 + 16 * q) % LP);
;             const int rs = psamp ? -1 : (pos0 == 0 ? 0 : (LP - pos0 < 16 ? LP - pos0 : -1));
;             float hh = 0.f;
; #pragma unroll
;             for (int r = 0; r < 4; ++r) hh = fa[r * 128 + cs] * hh + fb[r * 128 + cs];
; #pragma unroll
;             for (int j = 0; j < 3; ++j) if (j < q) hh = pqa[j] * hh + pqb[j];
; #pragma unroll
;             for (int i = 0; i < 16; ++i) {
;                 const float a2 = psa[(16 * q + i) * 128 + cs], b2 = psb[(16 * q + i) * 128 + cs];
;                 const bool reset = psamp ? ((i & 3) == 0) : (i == rs);
;                 float h0 = 0.f; if (psamp && reset) h0 = P.in[I_SLRU][(size_t)(l * 128 + ((pt0 + 16 * q - NPT) >> 2) + (i >> 2)) * 1024 + cgs];
;                 hh = reset ? a2 * h0 + b2 : a2 * hh + b2;
;                 psb[(16 * q + i) * 128 + cs] = hh;
;             }
.LBB0_1204:
	v_lshl_add_u32 v6, v206, 2, s12
	ds_read2st64_b32 v[2:3], v6 offset0:68 offset1:196
	ds_read2st64_b32 v[22:23], v6 offset0:70 offset1:72
	ds_read2st64_b32 v[24:25], v6 offset0:198 offset1:200
	ds_read2st64_b32 v[26:27], v6 offset0:74 offset1:76
	ds_read2st64_b32 v[28:29], v6 offset0:202 offset1:204
	ds_read2st64_b32 v[30:31], v6 offset0:78 offset1:80
	ds_read2st64_b32 v[82:83], v6 offset0:206 offset1:208
	ds_read2st64_b32 v[84:85], v6 offset0:82 offset1:84
	ds_read2st64_b32 v[86:87], v6 offset0:210 offset1:212
	ds_read2st64_b32 v[186:187], v6 offset0:86 offset1:88
	ds_read2st64_b32 v[188:189], v6 offset0:214 offset1:216
	ds_read2st64_b32 v[226:227], v6 offset0:90 offset1:92
	ds_read2st64_b32 v[228:229], v6 offset0:218 offset1:220
	ds_read2st64_b32 v[242:243], v6 offset0:94 offset1:96
	ds_read2st64_b32 v[244:245], v6 offset0:98 offset1:222
	ds_read2st64_b32 v[246:247], v6 offset0:224 offset1:226
	ds_read_b32 v9, v207
	ds_read_b32 v4, v208
	ds_read_b32 v10, v209
	ds_read_b32 v5, v210
	ds_read_b32 v11, v211
	ds_read_b32 v7, v212
	ds_read_b32 v12, v213
	ds_read_b32 v8, v214
	v_add_u32_e32 v0, s44, v191
	v_ashrrev_i32_e32 v0, 2, v0
	v_cndmask_b32_e64 v1, 0, 1, s[82:83]
	v_add_u32_e32 v0, s40, v0
	v_cmp_ne_u32_e64 s[54:55], 1, v1
	s_andn2_b64 vcc, exec, s[82:83]
	v_mov_b32_e32 v1, 0
	s_cbranch_vccnz .LBB0_1206
	v_ashrrev_i32_e32 v1, 31, v0
	v_lshlrev_b64 v[14:15], 12, v[0:1]
	v_lshl_add_u64 v[14:15], v[170:171], 0, v[14:15]
	global_load_dword v1, v[14:15], off
	v_or_b32_e32 v20, 1, v0
	v_ashrrev_i32_e32 v21, 31, v20
	v_lshlrev_b64 v[20:21], 12, v[20:21]
	v_lshl_add_u64 v[20:21], v[170:171], 0, v[20:21]
	global_load_dword v17, v[20:21], off
	v_or_b32_e32 v20, 2, v0
	v_ashrrev_i32_e32 v21, 31, v20
	v_lshlrev_b64 v[20:21], 12, v[20:21]
	v_lshl_add_u64 v[20:21], v[170:171], 0, v[20:21]
	global_load_dword v18, v[20:21], off
	v_or_b32_e32 v20, 3, v0
	v_ashrrev_i32_e32 v21, 31, v20
	v_lshlrev_b64 v[20:21], 12, v[20:21]
	v_lshl_add_u64 v[20:21], v[170:171], 0, v[20:21]
	global_load_dword v19, v[20:21], off
.LBB0_1206:
	s_waitcnt lgkmcnt(6)
	v_fmac_f32_e32 v4, 0, v9
	s_waitcnt lgkmcnt(4)
	v_fmac_f32_e32 v5, v4, v10
	s_waitcnt lgkmcnt(2)
	v_fmac_f32_e32 v7, v5, v11
	s_waitcnt lgkmcnt(0)
	v_fmac_f32_e32 v8, v7, v12
	v_fma_f32 v4, v172, v8, v157
	v_cndmask_b32_e64 v4, v8, v4, s[36:37]
	v_fma_f32 v5, v173, v4, v174
	v_cndmask_b32_e64 v4, v4, v5, s[30:31]
	v_fma_f32 v5, v156, v4, v175
	v_cndmask_b32_e64 v4, v4, v5, s[20:21]
	s_waitcnt vmcnt(0)
	v_cndmask_b32_e64 v1, v4, v1, s[0:1]
	v_fmac_f32_e32 v3, v2, v1
	v_fma_f32 v1, v22, v3, v24
	ds_write2st64_b32 v6, v3, v1 offset0:196 offset1:198
	v_fmac_f32_e32 v25, v23, v1
	v_fma_f32 v1, v25, v26, v28
	ds_write2st64_b32 v6, v25, v1 offset0:200 offset1:202
	v_cndmask_b32_e64 v1, v17, v1, s[54:55]
	v_fmac_f32_e32 v29, v27, v1
	v_fma_f32 v1, v30, v29, v82
	ds_write2st64_b32 v6, v29, v1 offset0:204 offset1:206
	v_fmac_f32_e32 v83, v31, v1
	v_fma_f32 v1, v83, v84, v86
	ds_write2st64_b32 v6, v83, v1 offset0:208 offset1:210
	v_cndmask_b32_e64 v1, v18, v1, s[54:55]
	v_fmac_f32_e32 v87, v85, v1
	v_fma_f32 v1, v186, v87, v188
	ds_write2st64_b32 v6, v87, v1 offset0:212 offset1:214
	v_fmac_f32_e32 v189, v187, v1
	v_fma_f32 v1, v189, v226, v228
	ds_write2st64_b32 v6, v189, v1 offset0:216 offset1:218
	v_cndmask_b32_e64 v1, v19, v1, s[54:55]
	v_fmac_f32_e32 v229, v227, v1
	v_fma_f32 v0, v242, v229, v245
	ds_write2st64_b32 v6, v229, v0 offset0:220 offset1:222
	v_fma_f32 v0, v0, v243, v246
	v_fmac_f32_e32 v247, v0, v244
	ds_write2st64_b32 v6, v0, v247 offset0:224 offset1:226
